# v137 + S5 gelu argument as x*(c1*x^2+k) (3 ops) + attention carry products without packed ops/copies
# speedup vs baseline: 1.0061x; 1.0035x over previous
; #define LAS __attribute__((address_space(3)))
; __device__ __forceinline__ void attn_unit(LAS unsigned char* lds, const bf16_t* Qm, const bf16_t* Km, const bf16_t* VT, const bf16_t* GBm, bf16_t* YB, int b, int hp, int qb) {
;     ...
;         if (k0 < qw + 15 && !__all(Rs == 0.f)) {
;             f32x4 s[4];
; #pragma unroll
;             for (int rb = 0; rb < 4; ++rb) {
;                 const int c = rb >> 1, e = rb & 1;
;                 const int kl = 32 * c + (fr >> 2) * 8 + e * 4 + (fr & 3);
;                 s[rb] = (f32x4){0.f, 0.f, 0.f, 0.f};
; #pragma unroll
;                 for (int ks = 0; ks < 4; ++ks) {
;                     const bf16x8 a = *(const LAS bf16x8*)(KL + kl * 272 + (ks * 32 + fq * 8) * 2);
;                     s[rb] = __builtin_amdgcn_mfma_f32_16x16x32_bf16(a, qf[ks], s[rb], 0, 0, 0);
;                 }
;             }
;             const int qi = qw + fr;
;             float be[2][8], om[2][8];
; #pragma unroll
;             for (int c = 0; c < 2; ++c)
; #pragma unroll
;                 for (int i = 0; i < 8; ++i) {
;                     const float z = s[2 * c + (i >> 2)][i & 3];
;                     const int key = k0 + 32 * c + 8 * fq + i;
;                     const float e = __builtin_amdgcn_exp2f(-fabsf(z));
;                     const float r = __builtin_amdgcn_rcpf(1.0f + e);
;                     const bool pos = z >= 0.f, valid = key < qi;
;                     be[c][i] = valid ? (pos ? r : e * r) : 0.f;
;                     om[c][i] = valid ? (pos ? e * r : r) : 1.f;
;                 }
;             float suf[2][8], Gs[2], Tt[2];
; #pragma unroll
;             for (int c = 0; c < 2; ++c) {
;                 float run = 1.f;
; #pragma unroll
;                 for (int i = 7; i >= 0; --i) { suf[c][i] = run; run *= om[c][i]; }
;                 const float t1 = __shfl(run, (lane + 16) & 63), t2 = __shfl(run, (lane + 32) & 63), t3 = __shfl(run, (lane + 48) & 63);
;                 Gs[c] = (fq < 3 ? t1 : 1.f) * (fq < 2 ? t2 : 1.f) * (fq < 1 ? t3 : 1.f);
;                 Tt[c] = (run * t1) * (t2 * t3);
;             }
.Lattn_nomask:
	ds_read_b128 v[120:123], v116
	ds_read_b128 v[124:127], v116 offset:64
	ds_read_b128 v[128:131], v116 offset:1088
	ds_read_b128 v[132:135], v116 offset:1152
	s_waitcnt lgkmcnt(3)
	v_mfma_f32_16x16x32_bf16 v[120:123], v[120:123], v[0:3], 0
	s_waitcnt lgkmcnt(2)
	v_mfma_f32_16x16x32_bf16 v[120:123], v[124:127], v[4:7], v[120:123]
	ds_read_b128 v[124:127], v116 offset:128
	ds_read_b128 v[136:139], v116 offset:192
	s_waitcnt lgkmcnt(3)
	v_mfma_f32_16x16x32_bf16 v[128:131], v[128:131], v[0:3], 0
	s_waitcnt lgkmcnt(1)
	v_mfma_f32_16x16x32_bf16 v[120:123], v[124:127], v[8:11], v[120:123]
	ds_read_b128 v[124:127], v116 offset:1216
	ds_read_b128 v[140:143], v116 offset:1280
	ds_read_b128 v[144:147], v116 offset:8704
	ds_read_b128 v[148:151], v116 offset:8768
	v_mfma_f32_16x16x32_bf16 v[128:131], v[132:135], v[4:7], v[128:131]
	ds_read_b128 v[132:135], v116 offset:8832
	ds_read_b128 v[152:155], v116 offset:8896
	ds_read_b128 v[156:159], v116 offset:9792
	ds_read_b128 v[160:163], v116 offset:9856
	s_waitcnt lgkmcnt(8)
	v_mfma_f32_16x16x32_bf16 v[120:123], v[136:139], v[12:15], v[120:123]
	ds_read_b128 v[136:139], v116 offset:9920
	ds_read_b128 v[164:167], v116 offset:9984
	s_waitcnt lgkmcnt(9)
	v_mfma_f32_16x16x32_bf16 v[124:127], v[124:127], v[8:11], v[128:131]
	s_nop 3
	v_exp_f32_e32 v97, v120
	s_nop 0
	v_add_f32_e32 v101, 1.0, v97
	s_waitcnt lgkmcnt(7)
	v_mfma_f32_16x16x32_bf16 v[128:131], v[144:147], v[0:3], 0
	v_rcp_f32_e32 v168, v101
	s_nop 0
	v_mul_f32_e32 v101, v97, v168
	s_waitcnt lgkmcnt(6)
	v_mfma_f32_16x16x32_bf16 v[128:131], v[148:151], v[4:7], v[128:131]
	v_mfma_f32_16x16x32_bf16 v[124:127], v[140:143], v[12:15], v[124:127]
	v_exp_f32_e32 v142, v121
	v_exp_f32_e32 v143, v122
	s_waitcnt lgkmcnt(5)
	v_mfma_f32_16x16x32_bf16 v[128:131], v[132:135], v[8:11], v[128:131]
	v_add_f32_e32 v103, 1.0, v142
	v_rcp_f32_e32 v103, v103
	s_waitcnt lgkmcnt(3)
	v_mfma_f32_16x16x32_bf16 v[132:135], v[156:159], v[0:3], 0
	v_add_f32_e32 v120, 1.0, v143
	v_rcp_f32_e32 v120, v120
	s_waitcnt lgkmcnt(2)
	v_mfma_f32_16x16x32_bf16 v[132:135], v[160:163], v[4:7], v[132:135]
	s_waitcnt lgkmcnt(1)
	v_mfma_f32_16x16x32_bf16 v[132:135], v[136:139], v[8:11], v[132:135]
	v_exp_f32_e32 v144, v123
	v_exp_f32_e32 v145, v124
	v_add_f32_e32 v121, 1.0, v144
	v_rcp_f32_e32 v121, v121
	v_add_f32_e32 v122, 1.0, v145
	v_rcp_f32_e32 v122, v122
	v_mfma_f32_16x16x32_bf16 v[128:131], v[152:155], v[12:15], v[128:131]
	s_nop 0
	s_nop 0
	v_exp_f32_e32 v146, v125
	s_nop 0
	v_add_f32_e32 v123, 1.0, v146
	v_rcp_f32_e32 v123, v123
	s_nop 0
	s_nop 0
	v_exp_f32_e32 v138, v128
	v_exp_f32_e32 v131, v131
	v_exp_f32_e32 v126, v126
	s_nop 0
	v_add_f32_e32 v124, 1.0, v126
	v_rcp_f32_e32 v124, v124
	s_waitcnt lgkmcnt(0)
	v_mfma_f32_16x16x32_bf16 v[132:135], v[164:167], v[12:15], v[132:135]
	v_exp_f32_e32 v127, v127
	s_nop 0
	v_add_f32_e32 v125, 1.0, v127
	v_rcp_f32_e32 v147, v125
	v_add_f32_e32 v136, 1.0, v138
	v_rcp_f32_e32 v140, v136
	v_exp_f32_e32 v129, v129
	v_exp_f32_e32 v130, v130
	v_mul_f32_e32 v128, v138, v140
	v_add_f32_e32 v125, 1.0, v129
	v_add_f32_e32 v136, 1.0, v130
	v_add_f32_e32 v137, 1.0, v131
	v_rcp_f32_e32 v125, v125
	v_rcp_f32_e32 v141, v136
	v_rcp_f32_e32 v148, v137
	v_mul_f32_e32 v153, v147, v124
	v_mul_f32_e32 v154, v123, v153
	v_mul_f32_e32 v155, v122, v154
	v_exp_f32_e32 v132, v132
	v_exp_f32_e32 v133, v133
	v_exp_f32_e32 v134, v134
	v_exp_f32_e32 v99, v135
	v_mul_f32_e32 v156, v121, v155
	v_add_f32_e32 v136, 1.0, v132
	v_add_f32_e32 v137, 1.0, v133
	v_add_f32_e32 v138, 1.0, v134
	v_add_f32_e32 v139, 1.0, v99
	v_rcp_f32_e32 v149, v136
	v_rcp_f32_e32 v150, v137
	v_rcp_f32_e32 v152, v138
	v_rcp_f32_e32 v151, v139
	v_mul_f32_e32 v157, v120, v156
	v_mul_f32_e32 v103, v103, v157
	v_mul_f32_e32 v136, v168, v103
	v_or_b32_e32 v135, v105, v107
	v_lshlrev_b32_e32 v135, 2, v135
	v_xor_b32_e32 v135, 0x80, v135
	v_mul_f32_e32 v152, v151, v152
	ds_bpermute_b32 v137, v135, v136
	ds_bpermute_b32 v138, v118, v136
	v_mul_f32_e32 v150, v150, v152
	v_mul_f32_e32 v149, v149, v150
	v_mul_f32_e32 v148, v148, v149
	v_mul_f32_e32 v158, v141, v148
	v_mul_f32_e32 v159, v125, v158
	ds_bpermute_b32 v139, v119, v136
	s_waitcnt lgkmcnt(2)
	v_cndmask_b32_e64 v97, 1.0, v137, s[10:11]
	s_waitcnt lgkmcnt(1)
; #define LAS __attribute__((address_space(3)))
; __device__ __forceinline__ unsigned cvt_pk_bf16(float lo, float hi) { unsigned r; asm volatile("v_cvt_pk_bf16_f32 %0, %1, %2" : "=v"(r) : "v"(lo), "v"(hi)); return r; }
; __device__ __forceinline__ void attn_unit(LAS unsigned char* lds, const bf16_t* Qm, const bf16_t* Km, const bf16_t* VT, const bf16_t* GBm, bf16_t* YB, int b, int hp, int qb) {
;     ...
;                 const float t1 = __shfl(run, (lane + 16) & 63), t2 = __shfl(run, (lane + 32) & 63), t3 = __shfl(run, (lane + 48) & 63);
;                 Gs[c] = (fq < 3 ? t1 : 1.f) * (fq < 2 ? t2 : 1.f) * (fq < 1 ? t3 : 1.f);
;                 Tt[c] = (run * t1) * (t2 * t3);
;             }
;             bf16x8 pf[2];
; #pragma unroll
;             for (int c = 0; c < 2; ++c) {
;                 const float basec = Rs * Gs[c] * (c == 0 ? Tt[1] : 1.f);
;                 float w[8];
; #pragma unroll
;                 for (int i = 0; i < 8; ++i) w[i] = be[c][i] * (suf[c][i] * basec);
;                 u32x4 pw; pw.x = cvt_pk_bf16(w[0], w[1]); pw.y = cvt_pk_bf16(w[2], w[3]); pw.z = cvt_pk_bf16(w[4], w[5]); pw.w = cvt_pk_bf16(w[6], w[7]);
;                 pf[c] = __builtin_bit_cast(bf16x8, pw);
;             }
;             Rs *= Tt[0] * Tt[1];
; #pragma unroll
;             for (int db = 0; db < 8; ++db)
; #pragma unroll
;                 for (int c = 0; c < 2; ++c) {
;                     const bf16x8 a = *(const LAS bf16x8*)(VL + (db * 16 + fr) * 144 + (32 * c + 8 * fq) * 2);
;                     o[db] = __builtin_amdgcn_mfma_f32_16x16x32_bf16(a, pf[c], o[db], 0, 0, 0);
;                 }
	v_cndmask_b32_e64 v120, v138, 1.0, s[0:1]
	v_mul_f32_e32 v121, v140, v159
	v_mul_f32_e32 v97, v120, v97
	ds_bpermute_b32 v120, v135, v121
	ds_bpermute_b32 v123, v118, v121
	ds_bpermute_b32 v122, v119, v121
	s_waitcnt lgkmcnt(3)
	v_cndmask_b32_e64 v124, 1.0, v139, s[4:5]
	v_mul_f32_e32 v124, v97, v124
	s_waitcnt lgkmcnt(2)
	v_cndmask_b32_e64 v97, 1.0, v120, s[10:11]
	s_waitcnt lgkmcnt(1)
	v_cndmask_b32_e64 v125, v123, 1.0, s[0:1]
	v_mul_f32_e32 v97, v125, v97
	s_waitcnt lgkmcnt(0)
	v_cndmask_b32_e64 v125, 1.0, v122, s[4:5]
	v_mul_f32_e32 v120, v120, v122
	v_mul_f32_e32 v121, v121, v123
	v_mul_f32_e32 v135, v97, v125
	v_mul_f32_e32 v140, v96, v124
	v_mul_f32_e32 v141, v120, v121
	v_mul_f32_e32 v97, v140, v141
	v_mul_f32_e32 v120, v103, v97
	v_mul_f32_e32 v101, v101, v120
	v_mul_f32_e32 v103, v142, v120
	v_mul_f32_e32 v120, v157, v97
	v_mul_f32_e32 v121, v143, v120
	v_mul_f32_e32 v120, v156, v97
	v_mul_f32_e32 v122, v144, v120
	v_mul_f32_e32 v120, v155, v97
	v_mul_f32_e32 v123, v145, v120
	v_mul_f32_e32 v120, v154, v97
	v_mul_f32_e32 v124, v146, v120
	v_mul_f32_e32 v120, v153, v97
	v_mul_f32_e32 v125, v126, v120
	v_mul_f32_e32 v120, v147, v97
	v_mul_f32_e32 v97, v127, v120
	v_cvt_pk_bf16_f32 v120, v101, v103
	v_cvt_pk_bf16_f32 v121, v121, v122
	v_cvt_pk_bf16_f32 v122, v123, v124
	v_cvt_pk_bf16_f32 v123, v125, v97
	v_mul_f32_e32 v97, v96, v135
	v_mul_f32_e32 v124, v97, v159
	v_mul_f32_e32 v101, v128, v124
	v_mul_f32_e32 v103, v129, v124
	v_mul_f32_e32 v124, v97, v158
	v_mul_f32_e32 v125, v130, v124
	v_mul_f32_e32 v124, v97, v148
	v_mul_f32_e32 v126, v131, v124
	v_mul_f32_e32 v124, v97, v149
	v_mul_f32_e32 v127, v132, v124
	v_mul_f32_e32 v124, v97, v150
	v_mul_f32_e32 v128, v133, v124
	v_mul_f32_e32 v124, v97, v152
	v_mul_f32_e32 v129, v134, v124
	v_mul_f32_e32 v124, v151, v97
	v_mul_f32_e32 v97, v99, v124
	v_cvt_pk_bf16_f32 v124, v101, v103
	v_cvt_pk_bf16_f32 v125, v125, v126
	v_cvt_pk_bf16_f32 v126, v127, v128
	v_cvt_pk_bf16_f32 v127, v129, v97
	ds_read_b128 v[128:131], v117 offset:17408
	ds_read_b128 v[132:135], v117 offset:17472
	s_waitcnt lgkmcnt(1)
	v_mfma_f32_16x16x32_bf16 v[60:63], v[128:131], v[120:123], v[60:63]
	ds_read_b128 v[128:131], v117 offset:19712
	s_waitcnt lgkmcnt(1)
	v_mfma_f32_16x16x32_bf16 v[60:63], v[132:135], v[124:127], v[60:63]
	ds_read_b128 v[132:135], v117 offset:19776
	s_waitcnt lgkmcnt(1)
	v_mfma_f32_16x16x32_bf16 v[72:75], v[128:131], v[120:123], v[72:75]
	ds_read_b128 v[128:131], v117 offset:22016
	s_waitcnt lgkmcnt(1)
	v_mfma_f32_16x16x32_bf16 v[72:75], v[132:135], v[124:127], v[72:75]
	ds_read_b128 v[132:135], v117 offset:22080
	s_waitcnt lgkmcnt(1)
	v_mfma_f32_16x16x32_bf16 v[56:59], v[128:131], v[120:123], v[56:59]
	ds_read_b128 v[128:131], v117 offset:24320
	s_waitcnt lgkmcnt(1)
	v_mfma_f32_16x16x32_bf16 v[56:59], v[132:135], v[124:127], v[56:59]
	ds_read_b128 v[132:135], v117 offset:24384
	s_waitcnt lgkmcnt(1)
	v_mfma_f32_16x16x32_bf16 v[44:47], v[128:131], v[120:123], v[44:47]
	ds_read_b128 v[128:131], v117 offset:26624
	s_waitcnt lgkmcnt(1)
	v_mfma_f32_16x16x32_bf16 v[44:47], v[132:135], v[124:127], v[44:47]
	ds_read_b128 v[132:135], v117 offset:26688
	s_waitcnt lgkmcnt(1)
	v_mfma_f32_16x16x32_bf16 v[32:35], v[128:131], v[120:123], v[32:35]
	ds_read_b128 v[128:131], v117 offset:28928
	s_waitcnt lgkmcnt(1)
	v_mfma_f32_16x16x32_bf16 v[32:35], v[132:135], v[124:127], v[32:35]
	ds_read_b128 v[132:135], v117 offset:28992
	s_waitcnt lgkmcnt(1)
	v_mfma_f32_16x16x32_bf16 v[24:27], v[128:131], v[120:123], v[24:27]
	ds_read_b128 v[128:131], v117 offset:31232
	s_waitcnt lgkmcnt(1)
	v_mfma_f32_16x16x32_bf16 v[24:27], v[132:135], v[124:127], v[24:27]
	ds_read_b128 v[132:135], v117 offset:31296
	s_waitcnt lgkmcnt(1)
	v_mfma_f32_16x16x32_bf16 v[20:23], v[128:131], v[120:123], v[20:23]
	ds_read_b128 v[128:131], v117 offset:33536
	s_waitcnt lgkmcnt(1)
	v_mfma_f32_16x16x32_bf16 v[20:23], v[132:135], v[124:127], v[20:23]
	ds_read_b128 v[132:135], v117 offset:33600
	s_waitcnt lgkmcnt(1)
	v_mfma_f32_16x16x32_bf16 v[16:19], v[128:131], v[120:123], v[16:19]
	v_mul_f32_e64 v120, v136, v138
	v_mul_f32_e64 v121, v137, v139
	v_mul_f32_e32 v97, v120, v121
	s_waitcnt lgkmcnt(0)
	v_mfma_f32_16x16x32_bf16 v[16:19], v[132:135], v[124:127], v[16:19]
	v_mul_f32_e32 v97, v97, v141
	v_mul_f32_e32 v96, v96, v97

; #define LAS __attribute__((address_space(3)))
; template <bool PASSB>
; __device__ __forceinline__ void s5_phase(LAS unsigned char* lds, const Params& p) {
;     int tidl_ = threadIdx.x; asm volatile("" : "+v"(tidl_));
;     const int tid = tidl_, wave = tid >> 6, lane = tid & 63, fr = lane & 15, fq = lane >> 4;
;     unsigned char* ws = p.ws;
;     const bf16_t* U = (const bf16_t*)(ws + WS_XA); bf16_t* YG = (bf16_t*)(ws + WS_K);
;     float* AGG = (float*)(ws + WS_SAGG);
;     LAS float* BuL = (LAS float*)(lds + wave * 16384);
;     LAS unsigned char* HbL = lds + wave * 16384 + 10240;
;     const int gw = blockIdx.x * 8 + wave, NGW = gridDim.x * 8;
;     constexpr int NUNIT = NB * S5_NC * 64;
;     int curg = -1;
;     bf16x8 bfm[8], cfm[4], dfm; float are = 0.f, aim = 0.f, alre = 0.f, alim = 0.f;
;     const bf16x8 zero8 = (bf16x8){0, 0, 0, 0, 0, 0, 0, 0};
;     for (int un = gw; un < NUNIT; un += NGW) {
;         const int g = un & 63, c = (un >> 6) % S5_NC, b = un / (64 * S5_NC);
;         if (g != curg) { curg = g;
; #pragma unroll
;             for (int nb = 0; nb < 8; ++nb) bfm[nb] = (fq < 2) ? *(const bf16x8*)((const bf16_t*)(ws + WS_BBM) + ((size_t)g * 128 + nb * 16 + fr) * 16 + fq * 8) : zero8;
;             if (PASSB) {
; #pragma unroll
;                 for (int ks = 0; ks < 4; ++ks) cfm[ks] = *(const bf16x8*)((const bf16_t*)(ws + WS_CM) + ((size_t)g * 16 + fr) * 128 + ks * 32 + fq * 8);
;                 const unsigned dbits = f2bf(p.in[24][g * 16 + fr]);
;                 dfm = zero8;
; #pragma unroll
;                 for (int i = 0; i < 8; ++i) if (fq < 2 && fq * 8 + i == fr) dfm[i] = (short)dbits;
;             }
;             const f32x2 a = *(const f32x2*)((const float*)(ws + WS_ABAR) + (g * 64 + lane) * 2); are = a[0]; aim = a[1];
;             const f32x2 al = *(const f32x2*)((const float*)(ws + WS_ABARL) + (g * 64 + lane) * 2); alre = al[0]; alim = al[1];
;         }
;         float hr = 0.f, hi = 0.f;
;         if (PASSB) {
;             for (int j0 = 0; j0 < c; j0 += 8) {
;                 f32x2 e[8];
; #pragma unroll
;                 for (int i = 0; i < 8; ++i) { const int jj = (j0 + i < c) ? j0 + i : c - 1; e[i] = *(const f32x2*)(AGG + ((size_t)((b * S5_NC + jj) * 64 + g) * 64 + lane) * 2); }
; #pragma unroll
.LBB0_1059:
	s_or_b64 exec, exec, s[0:1]
	v_mov_b32_e32 v1, v226
	s_waitcnt lgkmcnt(0)
	s_barrier
	s_movk_i32 s0, 0x1000
	v_ashrrev_i32_e32 v0, 6, v1
	v_add_u32_e32 v102, s94, v0
	v_cmp_gt_i32_e32 vcc, s0, v102
	s_and_saveexec_b64 s[36:37], vcc
	s_cbranch_execz .LBB0_1096
	v_lshl_add_u32 v9, v0, 14, 0
	v_lshrrev_b32_e32 v0, 1, v1
	v_and_b32_e32 v11, 24, v0
	v_mov_b32_e32 v0, 0
	v_and_b32_e32 v72, 15, v1
	v_and_b32_e32 v2, 48, v1
	v_mov_b32_e32 v3, v0
	v_or_b32_e32 v13, 1, v11
	v_lshl_add_u64 v[4:5], s[78:79], 0, v[2:3]
	s_mov_b64 s[6:7], 0x130000
	v_cmp_eq_u32_e64 s[8:9], v13, v72
	v_or_b32_e32 v13, 2, v11
	v_and_b32_e32 v10, 63, v1
	v_lshl_add_u64 v[74:75], v[4:5], 0, s[6:7]
	s_mov_b64 s[6:7], 0x170000
	v_cmp_eq_u32_e64 s[10:11], v13, v72
	v_or_b32_e32 v13, 3, v11
	v_lshl_add_u64 v[76:77], v[4:5], 0, s[6:7]
	v_lshlrev_b32_e32 v4, 3, v10
	v_mov_b32_e32 v5, v0
	v_cmp_eq_u32_e64 s[12:13], v13, v72
	v_or_b32_e32 v13, 4, v11
	s_add_u32 s40, s78, 0x120000
	v_lshl_add_u64 v[78:79], s[4:5], 0, v[4:5]
	v_and_b32_e32 v4, 16, v1
	v_lshlrev_b32_e32 v6, 1, v72
	v_mov_b32_e32 v7, v0
	s_movk_i32 s4, 0x110
	v_cmp_eq_u32_e64 s[14:15], v13, v72
	v_or_b32_e32 v13, 5, v11
	s_addc_u32 s41, s79, 0
	v_lshrrev_b32_e32 v8, 6, v1
	v_cmp_gt_u32_e32 vcc, 32, v10
	v_cmp_lt_u32_e64 s[0:1], 31, v10
	v_lshlrev_b32_e32 v3, 1, v10
	v_lshl_add_u64 v[80:81], s[16:17], 0, v[4:5]
	v_lshl_add_u64 v[82:83], s[44:45], 0, v[6:7]
	v_mul_u32_u24_e32 v6, 0x50, v10
	v_lshlrev_b32_e32 v7, 2, v10
	v_mad_u32_u24 v10, v72, s4, v9
	v_cmp_eq_u32_e64 s[4:5], v11, v72
	v_cmp_eq_u32_e64 s[16:17], v13, v72
	v_or_b32_e32 v13, 6, v11
	v_or_b32_e32 v11, 7, v11
	v_lshrrev_b32_e32 v1, 2, v1
	s_add_u32 s46, s78, 0x128000
	v_add_u32_e32 v12, v9, v2
	v_cmp_eq_u32_e64 s[18:19], v13, v72
	v_cmp_eq_u32_e64 s[20:21], v11, v72
	v_mul_u32_u24_e32 v11, 0x50, v72
	v_lshl_add_u64 v[4:5], s[78:79], 0, v[4:5]
	s_mov_b64 s[6:7], 0x6000600
	v_and_b32_e32 v86, 12, v1
	v_mov_b32_e32 v1, v0
	s_addc_u32 s47, s79, 0
	v_lshlrev_b32_e32 v103, 7, v72
	v_mov_b32_e32 v73, v0
	v_lshlrev_b32_e32 v104, 4, v72
	s_and_b64 s[4:5], vcc, s[4:5]
	s_and_b64 s[8:9], vcc, s[8:9]
	s_and_b64 s[10:11], vcc, s[10:11]
	s_and_b64 s[12:13], vcc, s[12:13]
	s_and_b64 s[14:15], vcc, s[14:15]
	s_and_b64 s[16:17], vcc, s[16:17]
	s_and_b64 s[18:19], vcc, s[18:19]
	s_and_b64 s[20:21], vcc, s[20:21]
	v_lshl_add_u64 v[84:85], v[4:5], 0, s[6:7]
	v_add_u16_e32 v105, s94, v8
	v_mov_b32_e32 v87, v0
	v_mov_b32_e32 v111, -1
	s_mov_b64 s[62:63], 0
	s_movk_i32 s6, 0x7fff
	s_mov_b32 s7, 0xffff
	v_lshlrev_b32_e32 v106, 2, v3
	v_add_u32_e32 v107, v12, v11
	v_add_u32_e32 v108, v9, v6
	v_add_u32_e32 v109, v9, v7
	v_add_u32_e32 v110, v10, v2
	s_mov_b64 s[64:65], 0x200
	s_movk_i32 s22, 0xfff
	v_mov_b32_e32 v88, 0
	v_mov_b32_e32 v92, 0
	v_mov_b64_e32 v[90:91], v[0:1]
	v_mov_b32_e32 v192, 0xbdd2d3e7
	v_mov_b32_e32 v193, 0xc0135761
	s_branch .LBB0_1062

; #define LAS __attribute__((address_space(3)))
; __device__ __forceinline__ unsigned cvt_pk_bf16(float lo, float hi) { unsigned r; asm volatile("v_cvt_pk_bf16_f32 %0, %1, %2" : "=v"(r) : "v"(lo), "v"(hi)); return r; }
; template <bool PASSB>
; __device__ __forceinline__ void s5_phase(LAS unsigned char* lds, const Params& p) {
;     ...
;         for (int st = 0; st < NST; ++st) {
;             const size_t r0 = row0 + st * 16;
;             const bf16x8 au = au_q0; au_q0 = au_q1; au_q1 = au_q2;
;             if (st + 3 < NST) au_q2 = (fq < 2) ? *(const bf16x8*)(up + (size_t)(st + 3) * 16 * 16) : zero8;
; #pragma unroll
;             for (int nb = 0; nb < 8; ++nb) {
;                 const f32x4 d = __builtin_amdgcn_mfma_f32_16x16x32_bf16(au, bfm[nb], (f32x4){0.f, 0.f, 0.f, 0.f}, 0, 0, 0);
;                 *(LAS f32x4*)(BuL + (nb * 16 + fr) * 20 + fq * 4) = d;
;             }
;             LDS_WAIT();
;             f32x4 br4[4], bi4[4];
; #pragma unroll
;             for (int q = 0; q < 4; ++q) { br4[q] = *(const LAS f32x4*)(BuL + lane * 20 + q * 4); bi4[q] = *(const LAS f32x4*)(BuL + (64 + lane) * 20 + q * 4); }
; #pragma unroll
;             for (int t = 0; t < 16; ++t) {
;                 const float bur = br4[t >> 2][t & 3], bui = bi4[t >> 2][t & 3];
;                 const float nr = are * hr - aim * hi + bur, ni = are * hi + aim * hr + bui; hr = nr; hi = ni;
;                 if (PASSB) *(LAS unsigned*)(HbL + t * 272 + lane * 4) = cvt_pk_bf16(hr, hi);
;             }
;             if (PASSB) {
;                 LDS_WAIT();
;                 f32x4 y = __builtin_amdgcn_mfma_f32_16x16x32_bf16(au, dfm, (f32x4){0.f, 0.f, 0.f, 0.f}, 0, 0, 0);
; #pragma unroll
;                 for (int ks = 0; ks < 4; ++ks) {
;                     const bf16x8 a = *(const LAS bf16x8*)(HbL + fr * 272 + (ks * 32 + fq * 8) * 2);
;                     y = __builtin_amdgcn_mfma_f32_16x16x32_bf16(a, cfm[ks], y, 0, 0, 0);
;                 }
; #pragma unroll
;                 for (int j = 0; j < 4; ++j) {
;                     const float v = y[j];
;                     const float ge = v * sigmoidf_(1.5957691216057308f * (v + 0.044715f * v * v * v));
;                     YG[(r0 + fq * 4 + j) * 1024 + g * 16 + fr] = (bf16_t)(cvt_pk_bf16(ge, ge) & 0xffffu);
;                 }
;             }
;             LDS_WAIT();
;         }
.LBB0_1093:
	s_or_b64 exec, exec, s[24:25]
	s_add_i32 s23, s23, 1
	v_lshl_add_u64 v[98:99], v[98:99], 0, s[64:65]
	s_cmp_eq_u32 s23, 32
	v_mfma_f32_16x16x32_bf16 v[68:71], v[68:71], v[52:55], 0
	s_waitcnt lgkmcnt(0)
	v_fmac_f32_e32 v112, v88, v94
	v_fmac_f32_e32 v128, v88, v95
	v_fma_f32 v112, -v92, v95, v112
	v_fmac_f32_e32 v128, v92, v94
	v_cvt_pk_bf16_f32 v1, v112, v128
	v_fmac_f32_e32 v113, v88, v112
	v_fmac_f32_e32 v129, v88, v128
	v_fma_f32 v113, -v92, v128, v113
	v_fmac_f32_e32 v129, v92, v112
	v_cvt_pk_bf16_f32 v152, v113, v129
	ds_write2_b32 v158, v1, v152 offset0:0 offset1:68
	v_mfma_f32_16x16x32_bf16 v[172:175], v[64:67], v[8:11], 0
	v_mfma_f32_16x16x32_bf16 v[176:179], v[64:67], v[4:7], 0
	v_fmac_f32_e32 v114, v88, v113
	v_fmac_f32_e32 v130, v88, v129
	v_fma_f32 v114, -v92, v129, v114
	v_fmac_f32_e32 v130, v92, v113
	v_cvt_pk_bf16_f32 v1, v114, v130
	v_fmac_f32_e32 v115, v88, v114
	v_fmac_f32_e32 v131, v88, v130
	v_fma_f32 v115, -v92, v130, v115
	v_fmac_f32_e32 v131, v92, v114
	v_cvt_pk_bf16_f32 v152, v115, v131
	ds_write2_b32 v158, v1, v152 offset0:136 offset1:204
	ds_write_b128 v107, v[172:175]
	v_mfma_f32_16x16x32_bf16 v[180:183], v[64:67], v[16:19], 0
	v_mfma_f32_16x16x32_bf16 v[184:187], v[64:67], v[12:15], 0
	ds_write_b128 v107, v[176:179] offset:1280
	v_fmac_f32_e32 v116, v88, v115
	v_fmac_f32_e32 v132, v88, v131
	v_fma_f32 v116, -v92, v131, v116
	v_fmac_f32_e32 v132, v92, v115
	v_cvt_pk_bf16_f32 v1, v116, v132
	v_fmac_f32_e32 v117, v88, v116
	v_fmac_f32_e32 v133, v88, v132
	v_fma_f32 v117, -v92, v132, v117
	v_fmac_f32_e32 v133, v92, v116
	v_cvt_pk_bf16_f32 v152, v117, v133
	ds_write2_b32 v159, v1, v152 offset0:0 offset1:68
	ds_write_b128 v107, v[180:183] offset:2560
	ds_write_b128 v107, v[184:187] offset:3840
	v_mfma_f32_16x16x32_bf16 v[188:191], v[64:67], v[20:23], 0
	v_mfma_f32_16x16x32_bf16 v[172:175], v[64:67], v[24:27], 0
	v_mfma_f32_16x16x32_bf16 v[176:179], v[64:67], v[28:31], 0
	v_fmac_f32_e32 v118, v88, v117
	v_fmac_f32_e32 v134, v88, v133
	v_fma_f32 v118, -v92, v133, v118
	v_fmac_f32_e32 v134, v92, v117
	v_cvt_pk_bf16_f32 v1, v118, v134
	v_fmac_f32_e32 v119, v88, v118
	v_fmac_f32_e32 v135, v88, v134
	v_fma_f32 v119, -v92, v134, v119
	v_fmac_f32_e32 v135, v92, v118
	v_cvt_pk_bf16_f32 v152, v119, v135
	ds_write2_b32 v159, v1, v152 offset0:136 offset1:204
	ds_write_b128 v107, v[188:191] offset:5120
	ds_write_b128 v107, v[172:175] offset:6400
	ds_write_b128 v107, v[176:179] offset:7680
	v_mfma_f32_16x16x32_bf16 v[172:175], v[64:67], v[32:35], 0
	v_fmac_f32_e32 v120, v88, v119
	v_fmac_f32_e32 v136, v88, v135
	v_fma_f32 v120, -v92, v135, v120
	v_fmac_f32_e32 v136, v92, v119
	v_cvt_pk_bf16_f32 v1, v120, v136
	v_fmac_f32_e32 v121, v88, v120
	v_fmac_f32_e32 v137, v88, v136
	v_fma_f32 v121, -v92, v136, v121
	v_fmac_f32_e32 v137, v92, v120
	v_cvt_pk_bf16_f32 v152, v121, v137
	ds_write2_b32 v160, v1, v152 offset0:0 offset1:68
	ds_write_b128 v107, v[172:175] offset:8960
	v_fmac_f32_e32 v122, v88, v121
	v_fmac_f32_e32 v138, v88, v137
	v_fma_f32 v122, -v92, v137, v122
	v_fmac_f32_e32 v138, v92, v121
	v_cvt_pk_bf16_f32 v1, v122, v138
	v_fmac_f32_e32 v123, v88, v122
	v_fmac_f32_e32 v139, v88, v138
	v_fma_f32 v123, -v92, v138, v123
	v_fmac_f32_e32 v139, v92, v122
	v_cvt_pk_bf16_f32 v152, v123, v139
	ds_write2_b32 v160, v1, v152 offset0:136 offset1:204
	v_fmac_f32_e32 v124, v88, v123
	v_fmac_f32_e32 v140, v88, v139
	v_fma_f32 v124, -v92, v139, v124
	v_fmac_f32_e32 v140, v92, v123
	v_cvt_pk_bf16_f32 v1, v124, v140
	v_fmac_f32_e32 v125, v88, v124
	v_fmac_f32_e32 v141, v88, v140
	v_fma_f32 v125, -v92, v140, v125
	v_fmac_f32_e32 v141, v92, v124
	v_cvt_pk_bf16_f32 v152, v125, v141
	ds_write2_b32 v161, v1, v152 offset0:0 offset1:68
	v_fmac_f32_e32 v126, v88, v125
	v_fmac_f32_e32 v142, v88, v141
	v_fma_f32 v126, -v92, v141, v126
	v_fmac_f32_e32 v142, v92, v125
	v_cvt_pk_bf16_f32 v1, v126, v142
	v_fmac_f32_e32 v127, v88, v126
	v_fmac_f32_e32 v143, v88, v142
	v_fma_f32 v127, -v92, v142, v127
	v_fmac_f32_e32 v143, v92, v126
	v_cvt_pk_bf16_f32 v152, v127, v143
	ds_write2_b32 v161, v1, v152 offset0:136 offset1:204
	v_mov_b32_e32 v94, v127
	v_mov_b32_e32 v95, v143
	s_waitcnt lgkmcnt(0)
	ds_read_b128 v[112:115], v110 offset:10240
	ds_read_b128 v[116:119], v110 offset:10304
	s_waitcnt lgkmcnt(1)
	v_mfma_f32_16x16x32_bf16 v[68:71], v[112:115], v[36:39], v[68:71]
	ds_read_b128 v[112:115], v110 offset:10368
	s_waitcnt lgkmcnt(1)
	v_mfma_f32_16x16x32_bf16 v[68:71], v[116:119], v[40:43], v[68:71]
	ds_read_b128 v[116:119], v110 offset:10432
	s_waitcnt lgkmcnt(1)
	v_mfma_f32_16x16x32_bf16 v[68:71], v[112:115], v[44:47], v[68:71]
	s_waitcnt lgkmcnt(0)
	v_mfma_f32_16x16x32_bf16 v[68:71], v[116:119], v[48:51], v[68:71]
	ds_read_b128 v[112:115], v108
	ds_read_b128 v[116:119], v108 offset:16
	ds_read_b128 v[120:123], v108 offset:32
	ds_read_b128 v[124:127], v108 offset:48
	ds_read_b128 v[128:131], v108 offset:5120
	ds_read_b128 v[132:135], v108 offset:5136
	ds_read_b128 v[136:139], v108 offset:5152
	ds_read_b128 v[140:143], v108 offset:5168
	s_nop 0
	v_mul_f32_e32 v148, v68, v68
	v_mul_f32_e32 v149, v69, v69
	v_mul_f32_e32 v150, v70, v70
	v_mul_f32_e32 v151, v71, v71
	v_fma_f32 v148, v148, v192, v193
	v_fma_f32 v149, v149, v192, v193
	v_fma_f32 v150, v150, v192, v193
	v_fma_f32 v151, v151, v192, v193
	v_mul_f32_e32 v148, v68, v148
	v_mul_f32_e32 v149, v69, v149
	v_mul_f32_e32 v150, v70, v150
	v_mul_f32_e32 v151, v71, v151
	v_exp_f32_e32 v148, v148
	v_exp_f32_e32 v149, v149
	v_exp_f32_e32 v150, v150
	v_exp_f32_e32 v151, v151
	v_add_f32_e32 v148, 1.0, v148
	v_add_f32_e32 v149, 1.0, v149
	v_add_f32_e32 v150, 1.0, v150
	v_add_f32_e32 v151, 1.0, v151
	v_rcp_f32_e32 v148, v148
	v_rcp_f32_e32 v149, v149
	v_rcp_f32_e32 v150, v150
	v_rcp_f32_e32 v151, v151
	v_mul_f32_e32 v148, v68, v148
	v_mul_f32_e32 v149, v69, v149
	v_mul_f32_e32 v150, v70, v150
	v_mul_f32_e32 v151, v71, v151
	v_cvt_pk_bf16_f32 v148, v148, v149
	v_cvt_pk_bf16_f32 v150, v150, v151
	global_store_short v[144:145], v148, off
	global_store_short_d16_hi v[144:145], v148, off offset:2048
	global_store_short v[146:147], v150, off
	global_store_short_d16_hi v[146:147], v150, off offset:2048
	v_lshl_add_u64 v[144:145], v[144:145], 0, s[82:83]
	v_lshl_add_u64 v[146:147], v[146:147], 0, s[82:83]
	s_waitcnt lgkmcnt(0)
	v_mov_b64_e32 v[70:71], v[66:67]
	v_mov_b64_e32 v[68:69], v[64:65]
	s_cbranch_scc1 .LBB0_1061
